# gate rows touched by group A three tiles before the item ends (after the last real K/V DMA), counted vmcnt(5) for the two following waits
# baseline (speedup 1.0000x reference)
; __device__ void diff_item(const Params& p, unsigned char* smem, bool sample, int b, int h, int qb, float lam) {
;     ...
;   if (!sample) {
;     const int s = qb * 128 + g * 32 + r;
;     tok = b * SEQ + s;
;     qpos = s - r;
;     ntw = 2 * qb + (g >> 1) + 1;
;     ntb = 2 * qb + 2;
;     nvalid = 64;
;     active = true; valid = true;
;     kbase = p.Kall + (size_t)b * SEQ * 1024 + h * 128;
;     vtbase = p.VTp + (size_t)(b * 1024 + h * 128) * SEQ;
;     vld = SEQ;
;   } else {
;     tok = NPROMPT + b * 16 + (r < 16 ? r : 15);
;     qpos = 1024;
;     ntw = 17; ntb = 17; nvalid = 16;
;     active = (g == 0); valid = (r < 16);
;     kbase = p.Kall + ((size_t)NPROMPT + (size_t)b * SKV) * 1024 + h * 128;
;     vtbase = p.VTs + (size_t)(b * 1024 + h * 128) * SKV;
;     vld = SKV;
;   }
;   const u16* qptr = p.Qb + (size_t)tok * 1024 + h * 128 + c * 64 + hh * 8;
.LBB0_344:
	s_or_b64 exec, exec, s[0:1]
	s_waitcnt lgkmcnt(0)
	s_barrier
	ds_read_b32 v0, v172
	s_movk_i32 s0, 0xff
	s_waitcnt lgkmcnt(0)
	s_barrier
	v_cmp_lt_i32_e32 vcc, s0, v0
	v_readfirstlane_b32 s6, v0
	s_mov_b64 s[0:1], -1
	s_cbranch_vccnz .LBB0_339
	v_mov_b32_e32 v175, v160
	s_ashr_i32 s62, s6, 1
	s_and_b32 s59, s6, 1
	v_readfirstlane_b32 s56, v175
	s_sub_i32 s0, 0x7f, s62
	s_bfe_u32 s39, s56, 0x20006
	s_or_b32 s57, s59, s33
	s_lshl_b32 s1, s0, 7
	s_lshl_b32 s6, s39, 5
	s_lshl_b32 s0, s0, 1
	v_and_b32_e32 v182, 31, v175
	s_ashr_i32 s64, s56, 8
	s_or_b32 s63, s6, s1
	s_or_b32 s58, s0, 1
	s_lshl_b32 s6, s57, 8
	v_or_b32_e32 v0, s34, v182
	s_add_u32 s14, s36, s6
	v_add_u32_e32 v0, s63, v0
	s_addc_u32 s15, s37, 0
	s_lshl_b32 s0, s57, 22
	s_or_b32 s0, s0, s35
	v_ashrrev_i32_e32 v1, 31, v0
	v_readlane_b32 s40, v255, 0
	s_add_u32 s20, s68, s0
	v_lshlrev_b64 v[164:165], 11, v[0:1]
	v_readlane_b32 s52, v255, 12
	v_readlane_b32 s53, v255, 13
	s_addc_u32 s21, s69, 0
	s_lshl_b32 s0, s64, 6
	v_lshl_add_u64 v[0:1], s[52:53], 0, v[164:165]
	v_bfe_u32 v174, v175, 5, 1
	v_lshl_add_u64 v[0:1], v[0:1], 0, s[6:7]
	s_ashr_i32 s1, s0, 31
	v_lshl_add_u64 v[0:1], s[0:1], 1, v[0:1]
	v_lshlrev_b32_e32 v162, 4, v174
	v_lshl_add_u64 v[2:3], v[0:1], 0, v[162:163]
	v_mov_b32_e32 v0, v160
	v_lshlrev_b32_e32 v252, 1, v164
	v_lshl_add_u32 v252, v174, 7, v252
	v_add_u32_e32 v252, s6, v252
	s_mov_b32 s61, 0
	global_load_dwordx4 v[128:131], v[2:3], off
	global_load_dwordx4 v[132:135], v[2:3], off offset:32
	global_load_dwordx4 v[136:139], v[2:3], off offset:64
	global_load_dwordx4 v[140:143], v[2:3], off offset:96
	v_readfirstlane_b32 s1, v0
	s_movk_i32 s0, 0xffc0
	s_cmp_eq_u32 s64, 1
	v_mov_b32_e32 v1, s1
	v_bfi_b32 v1, s0, v1, v0
	s_cselect_b64 s[12:13], -1, 0
	s_cmp_lg_u32 s64, 1
	v_ashrrev_i32_e32 v2, 4, v1
	v_lshrrev_b32_e32 v3, 4, v1
	v_lshlrev_b32_e32 v4, 11, v1
	v_add_u32_e32 v1, 0x200, v1
	s_cselect_b64 s[16:17], -1, 0
	s_lshl_b32 s0, s1, 4
	v_xor_b32_e32 v5, v2, v0
	v_lshlrev_b32_e32 v6, 11, v2
	v_xor_b32_e32 v2, v3, v0
	v_ashrrev_i32_e32 v3, 4, v1
	s_and_b32 s0, s0, 0xfffffc00
	v_lshlrev_b32_e32 v7, 4, v5
	v_lshlrev_b32_e32 v2, 3, v2
	v_xor_b32_e32 v5, v3, v0
	s_add_i32 s6, s0, 0
	v_lshlrev_b32_e32 v3, 11, v3
	v_and_b32_e32 v2, 56, v2
	v_lshlrev_b32_e32 v5, 4, v5
	v_and_or_b32 v162, v7, s3, v6
	s_mov_b32 m0, s6
	v_lshlrev_b32_e32 v1, 11, v1
	v_and_or_b32 v4, v4, s22, v2
	v_and_or_b32 v170, v5, s3, v3
	v_and_or_b32 v1, v1, s22, v2
	v_lshlrev_b32_e32 v166, 1, v4
	v_lshlrev_b32_e32 v168, 1, v1
	v_mov_b32_e32 v167, v163
	v_mov_b32_e32 v169, v163
	v_lshl_add_u64 v[2:3], s[20:21], 0, v[166:167]
	v_lshl_add_u64 v[4:5], s[20:21], 0, v[168:169]
	v_lshl_add_u64 v[2:3], v[2:3], 0, s[8:9]
	v_lshl_add_u64 v[4:5], v[4:5], 0, s[8:9]
	v_mov_b32_e32 v171, v163
	v_readlane_b32 s41, v255, 1
	v_readlane_b32 s42, v255, 2
	v_readlane_b32 s43, v255, 3
	v_readlane_b32 s44, v255, 4
	v_readlane_b32 s45, v255, 5
	v_readlane_b32 s46, v255, 6
	v_readlane_b32 s47, v255, 7
	v_readlane_b32 s48, v255, 8
	v_readlane_b32 s49, v255, 9
	v_readlane_b32 s50, v255, 10
	v_readlane_b32 s51, v255, 11
	v_readlane_b32 s54, v255, 14
	v_readlane_b32 s55, v255, 15
	s_nop 0
	s_nop 0
	global_load_lds_dwordx4 v162, s[14:15]
	s_add_i32 m0, s6, 0x2000
	s_nop 0
	global_load_lds_dwordx4 v170, s[14:15]
	s_add_i32 m0, s6, 0x4000
	s_nop 0
	global_load_lds_dwordx4 v166, s[20:21]
	s_add_i32 m0, s6, 0x6000
	s_nop 0
	global_load_lds_dwordx4 v168, s[20:21]
	s_add_i32 m0, s6, 0x8000
	s_add_u32 s0, s14, 0x20000
	s_addc_u32 s1, s15, 0
	global_load_lds_dwordx4 v162, s[0:1]
	s_add_i32 m0, s6, 0xa000
	s_and_b64 vcc, exec, s[12:13]
	global_load_lds_dwordx4 v170, s[0:1]
	s_add_i32 m0, s6, 0xc000
	s_mov_b64 s[0:1], -1
	global_load_lds_dwordx4 v[2:3], off
	s_add_i32 m0, s6, 0xe000
	s_nop 0
	global_load_lds_dwordx4 v[4:5], off
	s_min_u32 s65, s58, 2
	s_add_i32 m0, s6, 0x10000
	s_lshl_b32 s0, s65, 17
	s_add_u32 s0, s14, s0
	s_addc_u32 s1, s15, 0
	v_lshl_add_u64 v[2:3], s[0:1], 0, v[162:163]
	s_lshl_b32 s65, s65, 7
	global_load_lds_dwordx4 v[2:3], off
	s_add_i32 m0, s6, 0x12000
	v_lshl_add_u64 v[2:3], s[0:1], 0, v[170:171]
	s_add_u32 s0, s20, s65
	s_addc_u32 s1, s21, 0
	global_load_lds_dwordx4 v[2:3], off
	v_lshl_add_u64 v[2:3], s[0:1], 0, v[166:167]
	s_add_i32 m0, s6, 0x14000
	s_nop 0
	global_load_lds_dwordx4 v[2:3], off
	v_lshl_add_u64 v[2:3], s[0:1], 0, v[168:169]
	s_add_i32 m0, s6, 0x16000
	s_mov_b64 s[0:1], 0
	global_load_lds_dwordx4 v[2:3], off
	s_waitcnt vmcnt(8)

; #define D_BAR do { asm volatile("" ::: "memory"); __builtin_amdgcn_s_barrier(); asm volatile("" ::: "memory"); } while (0)
; DI void diff_core(unsigned char* smem, const u16* qptr, const u16* kbase, const u16* vtbase, int vld,
;                   int ntb, int ntw, int nvalid, int ks0, const float* lut, int qpos, bool active, bool grpB,
;                   f32x16 (&O)[4], float& l_out) {
;     ...
;       asm volatile("s_waitcnt vmcnt(4)" ::: "memory");
;       D_BAR;
;       { const int tn = t + 3; dma(tn < tlast ? tn : tlast, tn & 3); }
.LBB0_364:
	s_add_i32 s67, s64, 0x104
	s_min_i32 s67, s67, s58
	s_lshl_b32 s86, s67, 6
	s_and_b32 s85, s65, 0x18000
	s_ashr_i32 s87, s86, 31
	s_add_i32 s85, s6, s85
	s_lshl_b64 s[88:89], s[86:87], 11
	s_add_u32 s88, s14, s88
	s_addc_u32 s89, s15, s89
	s_cmp_eq_u32 s61, 0
	s_cbranch_scc1 .LA_w4
	s_cmp_gt_u32 s61, 2
	s_cbranch_scc1 .LA_w4
	s_add_i32 s61, s61, 1
	s_waitcnt vmcnt(5)
	s_branch .LA_wd

; DI int crow(int i, int hh) { return (i & 3) + 8 * (i >> 2) + 4 * hh; }
; DI void diff_core(unsigned char* smem, const u16* qptr, const u16* kbase, const u16* vtbase, int vld,
;                   int ntb, int ntw, int nvalid, int ks0, const float* lut, int qpos, bool active, bool grpB,
;                   f32x16 (&O)[4], float& l_out) {
;     ...
;     if (lut != nullptr && t >= ntw - 3) {
;       const int base = t * 64 - qpos + 191;
; #pragma unroll
;       for (int kb = 0; kb < 2; ++kb)
; #pragma unroll
;         for (int i = 0; i < 16; ++i) S[kb][i] += lut[base + kb * 32 + crow(i, hh)];
;     ...
;       { const int tn = t + 3; dma(tn < tlast ? tn : tlast, tn & 3); }
;       if (act_t) softmax(t);
.LA_wd:
	s_barrier
	s_mov_b32 m0, s85
	s_lshl_b64 s[86:87], s[86:87], 1
	global_load_lds_dwordx4 v162, s[88:89]
	s_add_i32 m0, s85, 0x2000
	s_add_u32 s86, s20, s86
	s_addc_u32 s87, s21, s87
	global_load_lds_dwordx4 v170, s[88:89]
	s_add_i32 m0, s85, 0x4000
	s_andn2_b64 vcc, exec, s[0:1]
	global_load_lds_dwordx4 v166, s[86:87]
	s_add_i32 m0, s85, 0x6000
	s_nop 0
	global_load_lds_dwordx4 v168, s[86:87]
	s_cmp_lg_u32 s61, 0
	s_cbranch_scc1 .LA_nj
	s_add_i32 s85, s64, 0x104
	s_cmp_le_i32 s85, s58
	s_cbranch_scc1 .LA_nj
	global_load_dword v253, v252, s[80:81]
	s_mov_b32 s61, 1
.LA_nj:
	s_cbranch_vccnz .LBB0_359
	s_cmp_lt_i32 s66, s17
	s_cbranch_scc1 .LBB0_367
	ds_read2_b32 v[144:145], v199 offset1:1
	ds_read2_b32 v[146:147], v199 offset0:16 offset1:17
	ds_read2_b32 v[148:149], v199 offset0:18 offset1:19
	ds_read2_b32 v[150:151], v199 offset0:24 offset1:25
	ds_read2_b32 v[152:153], v199 offset0:26 offset1:27
	ds_read2_b32 v[154:155], v199 offset0:2 offset1:3
	ds_read2_b32 v[156:157], v199 offset0:8 offset1:9
	ds_read2_b32 v[158:159], v199 offset0:10 offset1:11
	s_waitcnt lgkmcnt(0)
	v_pk_add_f32 v[96:97], v[96:97], v[144:145]
	v_pk_add_f32 v[110:111], v[110:111], v[152:153]
	v_pk_add_f32 v[108:109], v[108:109], v[150:151]
	v_pk_add_f32 v[106:107], v[106:107], v[148:149]
	v_pk_add_f32 v[104:105], v[104:105], v[146:147]
	v_pk_add_f32 v[102:103], v[102:103], v[158:159]
	v_pk_add_f32 v[100:101], v[100:101], v[156:157]
	v_pk_add_f32 v[98:99], v[98:99], v[154:155]
	ds_read2_b32 v[144:145], v199 offset0:32 offset1:33
	ds_read2_b32 v[146:147], v199 offset0:48 offset1:49
	ds_read2_b32 v[148:149], v199 offset0:50 offset1:51
	ds_read2_b32 v[150:151], v199 offset0:56 offset1:57
	ds_read2_b32 v[152:153], v199 offset0:58 offset1:59
	ds_read2_b32 v[154:155], v199 offset0:34 offset1:35
	ds_read2_b32 v[156:157], v199 offset0:40 offset1:41
	ds_read2_b32 v[158:159], v199 offset0:42 offset1:43
	s_waitcnt lgkmcnt(0)
	v_pk_add_f32 v[112:113], v[112:113], v[144:145]
	v_pk_add_f32 v[126:127], v[126:127], v[152:153]
	v_pk_add_f32 v[124:125], v[124:125], v[150:151]
	v_pk_add_f32 v[122:123], v[122:123], v[148:149]
	v_pk_add_f32 v[120:121], v[120:121], v[146:147]
	v_pk_add_f32 v[118:119], v[118:119], v[158:159]
	v_pk_add_f32 v[116:117], v[116:117], v[156:157]
	v_pk_add_f32 v[114:115], v[114:115], v[154:155]
